# P6 epilogue: the wait for the next unit's prefetched K-tiles moved from the epilogue head to just before its first store
# baseline (speedup 1.0000x reference)
;     __device__ __forceinline__ void operator()(const f32x4 (&acc)[2][2][4][2], const Unit& u, int wr, int wc, int fr, int fq) const {
;         float rsv[8];
; #pragma unroll
;         for (int idx = 0; idx < 8; ++idx) { const f32x4 q = *(const f32x4*)(rowss + (size_t)(u.pm * BM + (idx >> 2) * HALF + wr * 64 + (idx & 3) * 16 + fr) * 4); rsv[idx] = (q[0] + q[1]) + (q[2] + q[3]); }
; #pragma unroll
;         for (int ai = 0; ai < 2; ++ai)
; #pragma unroll
;             for (int m = 0; m < 4; ++m) {
;                 const int r = u.pm * BM + ai * HALF + wr * 64 + m * 16 + fr;
;                 const float rs = rsqrtf(rsv[ai * 4 + m] * (1.0f / DM) + EPS);
; #pragma unroll
;                 for (int bj = 0; bj < 2; ++bj) {
;                     f32x4 a = acc[ai][bj][m][0] * rs, b = acc[ai][bj][m][1] * rs;
; #pragma unroll
;                     for (int t = 0; t < 4; ++t) { a[t] = fmaxf(a[t], 0.f); a[t] *= a[t]; b[t] = fmaxf(b[t], 0.f); b[t] *= b[t]; }
;                     st8bf(U + (size_t)r * FF + u.pn * BM + wc * 64 + bj * 32 + 8 * fq, a, b);
;                 }
.Lrsl6_slow:
	v_lshl_add_u32 v202, s36, 8, v168
	v_ashrrev_i32_e32 v203, 31, v202
	v_or_b32_e32 v166, 16, v202
	v_lshl_add_u64 v[144:145], v[202:203], 4, s[10:11]
	v_ashrrev_i32_e32 v167, 31, v166
	v_or_b32_e32 v164, 32, v202
	v_lshl_add_u64 v[146:147], v[166:167], 4, s[10:11]
	global_load_dwordx4 v[152:155], v[144:145], off
	global_load_dwordx4 v[160:163], v[146:147], off
	v_ashrrev_i32_e32 v165, 31, v164
	v_or_b32_e32 v158, 48, v202
	v_lshl_add_u64 v[144:145], v[164:165], 4, s[10:11]
	v_ashrrev_i32_e32 v159, 31, v158
	v_lshl_add_u64 v[146:147], v[158:159], 4, s[10:11]
	global_load_dwordx4 v[176:179], v[144:145], off
	global_load_dwordx4 v[180:183], v[146:147], off
	v_add_u32_e32 v156, 0x80, v202
	v_ashrrev_i32_e32 v157, 31, v156
	v_add_u32_e32 v150, 0x90, v202
	v_lshl_add_u64 v[144:145], v[156:157], 4, s[10:11]
	v_ashrrev_i32_e32 v151, 31, v150
	v_lshl_add_u64 v[146:147], v[150:151], 4, s[10:11]
	global_load_dwordx4 v[184:187], v[144:145], off
	global_load_dwordx4 v[188:191], v[146:147], off
	v_add_u32_e32 v146, 0xa0, v202
	v_ashrrev_i32_e32 v147, 31, v146
	v_lshl_add_u64 v[144:145], v[146:147], 4, s[10:11]
	global_load_dwordx4 v[192:195], v[144:145], off
	v_add_u32_e32 v144, 0xb0, v202
	v_ashrrev_i32_e32 v145, 31, v144
	v_lshl_add_u64 v[148:149], v[144:145], 4, s[10:11]
	global_load_dwordx4 v[196:199], v[148:149], off
	s_waitcnt vmcnt(0)
.Lrsl6_join:
	v_mov_b64_e32 v[148:149], s[22:23]
	s_lshl_b32 s34, s34, 8
	s_ashr_i32 s35, s34, 31
	v_lshlrev_b64 v[202:203], 13, v[202:203]
	s_lshl_b64 s[34:35], s[34:35], 1
	v_lshl_add_u64 v[202:203], s[4:5], 0, v[202:203]
	v_lshl_add_u64 v[202:203], v[202:203], 0, s[34:35]
	v_lshl_add_u64 v[202:203], v[202:203], 0, s[12:13]
	v_lshl_add_u64 v[202:203], v[202:203], 0, v[136:137]
	s_waitcnt lgkmcnt(0)
	v_mov_b32_e32 v204, v153
	v_mov_b32_e32 v205, v154
	v_mov_b32_e32 v153, v155
	v_mov_b32_e32 v154, v161
	v_mov_b32_e32 v155, v162
	v_mov_b32_e32 v161, v163
	v_pk_add_f32 v[152:153], v[204:205], v[152:153]
	v_mov_b32_e32 v162, v177
	v_mov_b32_e32 v163, v178
	v_mov_b32_e32 v177, v179
	v_pk_add_f32 v[154:155], v[154:155], v[160:161]
	v_pk_add_f32 v[176:177], v[162:163], v[176:177]
	v_mov_b32_e32 v163, v152
	v_mov_b32_e32 v162, v154
	v_mov_b32_e32 v152, v155
	v_mov_b32_e32 v178, v181
	v_mov_b32_e32 v179, v182
	v_mov_b32_e32 v181, v183
	v_pk_add_f32 v[152:153], v[162:163], v[152:153]
	v_pk_add_f32 v[178:179], v[178:179], v[180:181]
	v_pk_fma_f32 v[180:181], v[152:153], s[20:21], v[148:149] op_sel_hi:[1,0,0]
	v_mov_b32_e32 v182, v185
	v_mul_f32_e32 v152, 0x4b800000, v181
	v_cmp_gt_f32_e32 vcc, s56, v181
	v_mov_b32_e32 v183, v186
	v_mov_b32_e32 v185, v187
	v_cndmask_b32_e32 v152, v181, v152, vcc
	v_rsq_f32_e32 v173, v152
	v_pk_add_f32 v[160:161], v[182:183], v[184:185]
	v_mov_b32_e32 v186, v189
	v_mov_b32_e32 v187, v190
	v_mul_f32_e32 v174, 0x45800000, v173
	v_cndmask_b32_e32 v174, v173, v174, vcc
	v_pk_mul_f32 v[126:127], v[126:127], v[174:175] op_sel_hi:[1,0]
	v_pk_mul_f32 v[124:125], v[124:125], v[174:175] op_sel_hi:[1,0]
	v_pk_mul_f32 v[122:123], v[122:123], v[174:175] op_sel_hi:[1,0]
	v_pk_mul_f32 v[120:121], v[120:121], v[174:175] op_sel_hi:[1,0]
	v_max_f32_e32 v124, 0, v124
	v_max_f32_e32 v120, 0, v120
	v_max_f32_e32 v125, 0, v125
	v_max_f32_e32 v121, 0, v121
	v_max_f32_e32 v126, 0, v126
	v_max_f32_e32 v122, 0, v122
	v_max_f32_e32 v127, 0, v127
	v_max_f32_e32 v123, 0, v123
	v_pk_mul_f32 v[124:125], v[124:125], v[124:125]
	v_pk_mul_f32 v[182:183], v[120:121], v[120:121]
	v_pk_mul_f32 v[126:127], v[126:127], v[126:127]
	v_pk_mul_f32 v[184:185], v[122:123], v[122:123]
	v_pk_mul_f32 v[114:115], v[114:115], v[174:175] op_sel_hi:[1,0]
	v_cvt_pk_bf16_f32 v120, v124, v125
	v_cvt_pk_bf16_f32 v121, v126, v127
	v_cvt_pk_bf16_f32 v122, v182, v183
	v_cvt_pk_bf16_f32 v123, v184, v185
	v_pk_mul_f32 v[116:117], v[116:117], v[174:175] op_sel_hi:[1,0]
	v_pk_mul_f32 v[112:113], v[112:113], v[174:175] op_sel_hi:[1,0]
	v_max_f32_e32 v114, 0, v114
	v_max_f32_e32 v115, 0, v115
	s_waitcnt vmcnt(0)
	global_store_dwordx4 v[202:203], v[120:123], off
	v_pk_mul_f32 v[118:119], v[118:119], v[174:175] op_sel_hi:[1,0]
	v_max_f32_e32 v116, 0, v116
	v_max_f32_e32 v112, 0, v112
	v_max_f32_e32 v117, 0, v117
	v_max_f32_e32 v113, 0, v113
	v_pk_mul_f32 v[122:123], v[114:115], v[114:115]
	v_mul_f32_e32 v114, 0x4b800000, v180
	v_cmp_gt_f32_e32 vcc, s56, v180
	v_pk_mul_f32 v[116:117], v[116:117], v[116:117]
	v_pk_mul_f32 v[120:121], v[112:113], v[112:113]
	v_max_f32_e32 v112, 0, v118
	v_max_f32_e32 v113, 0, v119
	v_cndmask_b32_e32 v114, v180, v114, vcc
	v_pk_mul_f32 v[118:119], v[112:113], v[112:113]
	v_cvt_pk_bf16_f32 v112, v116, v117
	v_rsq_f32_e32 v116, v114
	v_cvt_pk_bf16_f32 v113, v118, v119
	v_cvt_pk_bf16_f32 v114, v120, v121
	v_cvt_pk_bf16_f32 v115, v122, v123
	global_store_dwordx4 v[202:203], v[112:115], off offset:64
	v_mov_b32_e32 v189, v191
	v_pk_add_f32 v[162:163], v[186:187], v[188:189]
	v_mul_f32_e32 v112, 0x45800000, v116
	v_cndmask_b32_e32 v112, v116, v112, vcc
	v_pk_mul_f32 v[104:105], v[104:105], v[112:113] op_sel_hi:[1,0]
	v_pk_mul_f32 v[110:111], v[110:111], v[112:113] op_sel_hi:[1,0]
	v_max_f32_e32 v104, 0, v104
	v_max_f32_e32 v105, 0, v105
	v_lshlrev_b64 v[114:115], 13, v[166:167]
	v_pk_mul_f32 v[116:117], v[104:105], v[104:105]
	v_max_f32_e32 v104, 0, v110
	v_max_f32_e32 v105, 0, v111
	v_pk_mul_f32 v[108:109], v[108:109], v[112:113] op_sel_hi:[1,0]
	v_pk_mul_f32 v[106:107], v[106:107], v[112:113] op_sel_hi:[1,0]
	v_pk_mul_f32 v[110:111], v[104:105], v[104:105]
	v_lshl_add_u64 v[104:105], s[4:5], 0, v[114:115]
	v_max_f32_e32 v108, 0, v108
	v_max_f32_e32 v109, 0, v109
	v_max_f32_e32 v106, 0, v106
	v_max_f32_e32 v107, 0, v107
;     __device__ __forceinline__ void operator()(const f32x4 (&acc)[2][2][4][2], const Unit& u, int wr, int wc, int fr, int fq) const {
;     ...
; #pragma unroll
;         for (int ai = 0; ai < 2; ++ai)
; #pragma unroll
;             for (int m = 0; m < 4; ++m) {
;                 const int r = u.pm * BM + ai * HALF + wr * 64 + m * 16 + fr;
;                 const float rs = rsqrtf(rsv[ai * 4 + m] * (1.0f / DM) + EPS);
; #pragma unroll
;                 for (int bj = 0; bj < 2; ++bj) {
;                     f32x4 a = acc[ai][bj][m][0] * rs, b = acc[ai][bj][m][1] * rs;
; #pragma unroll
;                     for (int t = 0; t < 4; ++t) { a[t] = fmaxf(a[t], 0.f); a[t] *= a[t]; b[t] = fmaxf(b[t], 0.f); b[t] *= b[t]; }
;                     st8bf(U + (size_t)r * FF + u.pn * BM + wc * 64 + bj * 32 + 8 * fq, a, b);
;                 }
	v_lshl_add_u64 v[104:105], v[104:105], 0, s[34:35]
	v_pk_mul_f32 v[108:109], v[108:109], v[108:109]
	v_pk_mul_f32 v[118:119], v[106:107], v[106:107]
	v_lshl_add_u64 v[104:105], v[104:105], 0, s[12:13]
	v_pk_mul_f32 v[96:97], v[96:97], v[112:113] op_sel_hi:[1,0]
	v_lshl_add_u64 v[114:115], v[104:105], 0, v[136:137]
	v_cvt_pk_bf16_f32 v104, v108, v109
	v_cvt_pk_bf16_f32 v105, v110, v111
	v_cvt_pk_bf16_f32 v106, v116, v117
	v_cvt_pk_bf16_f32 v107, v118, v119
	v_pk_mul_f32 v[102:103], v[102:103], v[112:113] op_sel_hi:[1,0]
	v_pk_mul_f32 v[100:101], v[100:101], v[112:113] op_sel_hi:[1,0]
	v_pk_mul_f32 v[98:99], v[98:99], v[112:113] op_sel_hi:[1,0]
	v_max_f32_e32 v96, 0, v96
	v_max_f32_e32 v97, 0, v97
	global_store_dwordx4 v[114:115], v[104:107], off
	v_max_f32_e32 v100, 0, v100
	v_max_f32_e32 v101, 0, v101
	v_pk_mul_f32 v[104:105], v[96:97], v[96:97]
	v_max_f32_e32 v96, 0, v102
	v_max_f32_e32 v98, 0, v98
	v_max_f32_e32 v97, 0, v103
	v_max_f32_e32 v99, 0, v99
	v_pk_mul_f32 v[100:101], v[100:101], v[100:101]
	v_pk_mul_f32 v[102:103], v[96:97], v[96:97]
	v_pk_mul_f32 v[106:107], v[98:99], v[98:99]
	v_cvt_pk_bf16_f32 v96, v100, v101
	v_cvt_pk_bf16_f32 v97, v102, v103
	v_cvt_pk_bf16_f32 v98, v104, v105
	v_cvt_pk_bf16_f32 v99, v106, v107
	global_store_dwordx4 v[114:115], v[96:99], off offset:64
	v_mov_b32_e32 v190, v193
	v_mov_b32_e32 v191, v194
	v_mov_b32_e32 v98, v178
	v_mov_b32_e32 v99, v176
	v_mov_b32_e32 v176, v179
	v_pk_add_f32 v[98:99], v[98:99], v[176:177]
	v_lshlrev_b64 v[96:97], 13, v[164:165]
	v_pk_fma_f32 v[98:99], v[98:99], s[20:21], v[148:149] op_sel_hi:[1,0,0]
	v_lshl_add_u64 v[96:97], s[4:5], 0, v[96:97]
	v_mul_f32_e32 v100, 0x4b800000, v99
	v_cmp_gt_f32_e32 vcc, s56, v99
	v_lshl_add_u64 v[96:97], v[96:97], 0, s[34:35]
	v_lshl_add_u64 v[96:97], v[96:97], 0, s[12:13]
	v_cndmask_b32_e32 v99, v99, v100, vcc
	v_rsq_f32_e32 v99, v99
	v_lshl_add_u64 v[96:97], v[96:97], 0, v[136:137]
	v_mov_b32_e32 v193, v195
	v_mov_b32_e32 v194, v197
	v_mul_f32_e32 v100, 0x45800000, v99
	v_cndmask_b32_e32 v100, v99, v100, vcc
	v_pk_mul_f32 v[88:89], v[88:89], v[100:101] op_sel_hi:[1,0]
	v_pk_mul_f32 v[94:95], v[94:95], v[100:101] op_sel_hi:[1,0]
	v_pk_mul_f32 v[92:93], v[92:93], v[100:101] op_sel_hi:[1,0]
	v_pk_mul_f32 v[90:91], v[90:91], v[100:101] op_sel_hi:[1,0]
	v_max_f32_e32 v88, 0, v88
	v_max_f32_e32 v89, 0, v89
	v_max_f32_e32 v92, 0, v92
	v_max_f32_e32 v93, 0, v93
	v_pk_mul_f32 v[102:103], v[88:89], v[88:89]
	v_max_f32_e32 v88, 0, v94
	v_max_f32_e32 v90, 0, v90
	v_max_f32_e32 v89, 0, v95
	v_max_f32_e32 v91, 0, v91
	v_pk_mul_f32 v[92:93], v[92:93], v[92:93]
	v_pk_mul_f32 v[94:95], v[88:89], v[88:89]
	v_pk_mul_f32 v[104:105], v[90:91], v[90:91]
	v_pk_mul_f32 v[82:83], v[82:83], v[100:101] op_sel_hi:[1,0]
	v_cvt_pk_bf16_f32 v88, v92, v93
	v_cvt_pk_bf16_f32 v89, v94, v95
	v_cvt_pk_bf16_f32 v90, v102, v103
	v_cvt_pk_bf16_f32 v91, v104, v105
	v_pk_mul_f32 v[84:85], v[84:85], v[100:101] op_sel_hi:[1,0]
	v_pk_mul_f32 v[80:81], v[80:81], v[100:101] op_sel_hi:[1,0]
	v_max_f32_e32 v82, 0, v82
	v_max_f32_e32 v83, 0, v83
	global_store_dwordx4 v[96:97], v[88:91], off
	v_pk_mul_f32 v[86:87], v[86:87], v[100:101] op_sel_hi:[1,0]
	v_max_f32_e32 v84, 0, v84
	v_max_f32_e32 v80, 0, v80
	v_max_f32_e32 v85, 0, v85
	v_max_f32_e32 v81, 0, v81
	v_pk_mul_f32 v[90:91], v[82:83], v[82:83]
	v_mul_f32_e32 v82, 0x4b800000, v98
	v_cmp_gt_f32_e32 vcc, s56, v98
	v_pk_mul_f32 v[84:85], v[84:85], v[84:85]
	v_pk_mul_f32 v[88:89], v[80:81], v[80:81]
	v_max_f32_e32 v80, 0, v86
	v_max_f32_e32 v81, 0, v87
	v_cndmask_b32_e32 v82, v98, v82, vcc
	v_pk_mul_f32 v[86:87], v[80:81], v[80:81]
	v_cvt_pk_bf16_f32 v80, v84, v85
	v_rsq_f32_e32 v84, v82
	v_cvt_pk_bf16_f32 v81, v86, v87
	v_cvt_pk_bf16_f32 v82, v88, v89
	v_cvt_pk_bf16_f32 v83, v90, v91
	global_store_dwordx4 v[96:97], v[80:83], off offset:64
	v_mov_b32_e32 v195, v198
	v_mov_b32_e32 v197, v199
	v_mul_f32_e32 v80, 0x45800000, v84
	v_cndmask_b32_e32 v80, v84, v80, vcc
	v_pk_mul_f32 v[72:73], v[72:73], v[80:81] op_sel_hi:[1,0]
	v_pk_mul_f32 v[78:79], v[78:79], v[80:81] op_sel_hi:[1,0]
	v_max_f32_e32 v72, 0, v72
	v_max_f32_e32 v73, 0, v73
	v_lshlrev_b64 v[82:83], 13, v[158:159]
	v_pk_mul_f32 v[84:85], v[72:73], v[72:73]
	v_max_f32_e32 v72, 0, v78
	v_max_f32_e32 v73, 0, v79
	v_pk_mul_f32 v[76:77], v[76:77], v[80:81] op_sel_hi:[1,0]
	v_pk_mul_f32 v[74:75], v[74:75], v[80:81] op_sel_hi:[1,0]
	v_pk_mul_f32 v[78:79], v[72:73], v[72:73]
	v_lshl_add_u64 v[72:73], s[4:5], 0, v[82:83]
	v_max_f32_e32 v76, 0, v76
	v_max_f32_e32 v77, 0, v77
	v_max_f32_e32 v74, 0, v74
	v_max_f32_e32 v75, 0, v75
	v_lshl_add_u64 v[72:73], v[72:73], 0, s[34:35]
	v_pk_mul_f32 v[76:77], v[76:77], v[76:77]
	v_pk_mul_f32 v[86:87], v[74:75], v[74:75]
	v_lshl_add_u64 v[72:73], v[72:73], 0, s[12:13]
	v_pk_mul_f32 v[64:65], v[64:65], v[80:81] op_sel_hi:[1,0]
	v_lshl_add_u64 v[82:83], v[72:73], 0, v[136:137]
	v_cvt_pk_bf16_f32 v72, v76, v77
	v_cvt_pk_bf16_f32 v73, v78, v79
	v_cvt_pk_bf16_f32 v74, v84, v85
	v_cvt_pk_bf16_f32 v75, v86, v87
	v_pk_mul_f32 v[70:71], v[70:71], v[80:81] op_sel_hi:[1,0]
	v_pk_mul_f32 v[68:69], v[68:69], v[80:81] op_sel_hi:[1,0]
	v_pk_mul_f32 v[66:67], v[66:67], v[80:81] op_sel_hi:[1,0]
	v_max_f32_e32 v64, 0, v64
	v_max_f32_e32 v65, 0, v65
	global_store_dwordx4 v[82:83], v[72:75], off
	v_max_f32_e32 v68, 0, v68
	v_max_f32_e32 v69, 0, v69
	v_pk_mul_f32 v[72:73], v[64:65], v[64:65]
	v_max_f32_e32 v64, 0, v70
	v_max_f32_e32 v66, 0, v66
	v_max_f32_e32 v65, 0, v71
	v_max_f32_e32 v67, 0, v67
	v_pk_mul_f32 v[68:69], v[68:69], v[68:69]
	v_pk_mul_f32 v[70:71], v[64:65], v[64:65]
	v_pk_mul_f32 v[74:75], v[66:67], v[66:67]
	v_cvt_pk_bf16_f32 v64, v68, v69
;     __device__ __forceinline__ void operator()(const f32x4 (&acc)[2][2][4][2], const Unit& u, int wr, int wc, int fr, int fq) const {
;     ...
; #pragma unroll
;         for (int ai = 0; ai < 2; ++ai)
; #pragma unroll
;             for (int m = 0; m < 4; ++m) {
;                 const int r = u.pm * BM + ai * HALF + wr * 64 + m * 16 + fr;
;                 const float rs = rsqrtf(rsv[ai * 4 + m] * (1.0f / DM) + EPS);
; #pragma unroll
;                 for (int bj = 0; bj < 2; ++bj) {
;                     f32x4 a = acc[ai][bj][m][0] * rs, b = acc[ai][bj][m][1] * rs;
; #pragma unroll
;                     for (int t = 0; t < 4; ++t) { a[t] = fmaxf(a[t], 0.f); a[t] *= a[t]; b[t] = fmaxf(b[t], 0.f); b[t] *= b[t]; }
;                     st8bf(U + (size_t)r * FF + u.pn * BM + wc * 64 + bj * 32 + 8 * fq, a, b);
;                 }
	v_cvt_pk_bf16_f32 v65, v70, v71
	v_cvt_pk_bf16_f32 v66, v72, v73
	v_cvt_pk_bf16_f32 v67, v74, v75
	global_store_dwordx4 v[82:83], v[64:67], off offset:64
	v_pk_add_f32 v[152:153], v[190:191], v[192:193]
	v_pk_add_f32 v[154:155], v[194:195], v[196:197]
	v_mov_b32_e32 v66, v162
	v_mov_b32_e32 v67, v160
	v_mov_b32_e32 v160, v163
	v_pk_add_f32 v[66:67], v[66:67], v[160:161]
	v_lshlrev_b64 v[64:65], 13, v[156:157]
	v_pk_fma_f32 v[66:67], v[66:67], s[20:21], v[148:149] op_sel_hi:[1,0,0]
	v_lshl_add_u64 v[64:65], s[4:5], 0, v[64:65]
	v_mul_f32_e32 v68, 0x4b800000, v67
	v_cmp_gt_f32_e32 vcc, s56, v67
	v_lshl_add_u64 v[64:65], v[64:65], 0, s[34:35]
	v_lshl_add_u64 v[64:65], v[64:65], 0, s[12:13]
	v_cndmask_b32_e32 v67, v67, v68, vcc
	v_rsq_f32_e32 v67, v67
	v_lshl_add_u64 v[64:65], v[64:65], 0, v[136:137]
	v_mul_f32_e32 v68, 0x45800000, v67
	v_cndmask_b32_e32 v68, v67, v68, vcc
	v_pk_mul_f32 v[56:57], v[56:57], v[68:69] op_sel_hi:[1,0]
	v_pk_mul_f32 v[62:63], v[62:63], v[68:69] op_sel_hi:[1,0]
	v_pk_mul_f32 v[60:61], v[60:61], v[68:69] op_sel_hi:[1,0]
	v_pk_mul_f32 v[58:59], v[58:59], v[68:69] op_sel_hi:[1,0]
	v_max_f32_e32 v56, 0, v56
	v_max_f32_e32 v57, 0, v57
	v_max_f32_e32 v60, 0, v60
	v_max_f32_e32 v61, 0, v61
	v_pk_mul_f32 v[70:71], v[56:57], v[56:57]
	v_max_f32_e32 v56, 0, v62
	v_max_f32_e32 v58, 0, v58
	v_max_f32_e32 v57, 0, v63
	v_max_f32_e32 v59, 0, v59
	v_pk_mul_f32 v[60:61], v[60:61], v[60:61]
	v_pk_mul_f32 v[62:63], v[56:57], v[56:57]
	v_pk_mul_f32 v[72:73], v[58:59], v[58:59]
	v_pk_mul_f32 v[50:51], v[50:51], v[68:69] op_sel_hi:[1,0]
	v_cvt_pk_bf16_f32 v56, v60, v61
	v_cvt_pk_bf16_f32 v57, v62, v63
	v_cvt_pk_bf16_f32 v58, v70, v71
	v_cvt_pk_bf16_f32 v59, v72, v73
	v_pk_mul_f32 v[52:53], v[52:53], v[68:69] op_sel_hi:[1,0]
	v_pk_mul_f32 v[48:49], v[48:49], v[68:69] op_sel_hi:[1,0]
	v_max_f32_e32 v50, 0, v50
	v_max_f32_e32 v51, 0, v51
	global_store_dwordx4 v[64:65], v[56:59], off
	v_pk_mul_f32 v[54:55], v[54:55], v[68:69] op_sel_hi:[1,0]
	v_max_f32_e32 v52, 0, v52
	v_max_f32_e32 v48, 0, v48
	v_max_f32_e32 v53, 0, v53
	v_max_f32_e32 v49, 0, v49
	v_pk_mul_f32 v[58:59], v[50:51], v[50:51]
	v_mul_f32_e32 v50, 0x4b800000, v66
	v_cmp_gt_f32_e32 vcc, s56, v66
	v_pk_mul_f32 v[52:53], v[52:53], v[52:53]
	v_pk_mul_f32 v[56:57], v[48:49], v[48:49]
	v_max_f32_e32 v48, 0, v54
	v_max_f32_e32 v49, 0, v55
	v_cndmask_b32_e32 v50, v66, v50, vcc
	v_pk_mul_f32 v[54:55], v[48:49], v[48:49]
	v_cvt_pk_bf16_f32 v48, v52, v53
	v_rsq_f32_e32 v52, v50
	v_cvt_pk_bf16_f32 v49, v54, v55
	v_cvt_pk_bf16_f32 v50, v56, v57
	v_cvt_pk_bf16_f32 v51, v58, v59
	global_store_dwordx4 v[64:65], v[48:51], off offset:64
	s_nop 1
	v_mul_f32_e32 v48, 0x45800000, v52
	v_cndmask_b32_e32 v48, v52, v48, vcc
	v_pk_mul_f32 v[40:41], v[40:41], v[48:49] op_sel_hi:[1,0]
	v_pk_mul_f32 v[46:47], v[46:47], v[48:49] op_sel_hi:[1,0]
	v_max_f32_e32 v40, 0, v40
	v_max_f32_e32 v41, 0, v41
	v_lshlrev_b64 v[50:51], 13, v[150:151]
	v_pk_mul_f32 v[52:53], v[40:41], v[40:41]
	v_max_f32_e32 v40, 0, v46
	v_max_f32_e32 v41, 0, v47
	v_pk_mul_f32 v[44:45], v[44:45], v[48:49] op_sel_hi:[1,0]
	v_pk_mul_f32 v[42:43], v[42:43], v[48:49] op_sel_hi:[1,0]
	v_pk_mul_f32 v[46:47], v[40:41], v[40:41]
	v_lshl_add_u64 v[40:41], s[4:5], 0, v[50:51]
	v_max_f32_e32 v44, 0, v44
	v_max_f32_e32 v45, 0, v45
	v_max_f32_e32 v42, 0, v42
	v_max_f32_e32 v43, 0, v43
	v_lshl_add_u64 v[40:41], v[40:41], 0, s[34:35]
	v_pk_mul_f32 v[44:45], v[44:45], v[44:45]
	v_pk_mul_f32 v[54:55], v[42:43], v[42:43]
	v_lshl_add_u64 v[40:41], v[40:41], 0, s[12:13]
	v_pk_mul_f32 v[32:33], v[32:33], v[48:49] op_sel_hi:[1,0]
	v_lshl_add_u64 v[50:51], v[40:41], 0, v[136:137]
	v_cvt_pk_bf16_f32 v40, v44, v45
	v_cvt_pk_bf16_f32 v41, v46, v47
	v_cvt_pk_bf16_f32 v42, v52, v53
	v_cvt_pk_bf16_f32 v43, v54, v55
	v_pk_mul_f32 v[38:39], v[38:39], v[48:49] op_sel_hi:[1,0]
	v_pk_mul_f32 v[36:37], v[36:37], v[48:49] op_sel_hi:[1,0]
	v_pk_mul_f32 v[34:35], v[34:35], v[48:49] op_sel_hi:[1,0]
	v_max_f32_e32 v32, 0, v32
	v_max_f32_e32 v33, 0, v33
	global_store_dwordx4 v[50:51], v[40:43], off
	v_max_f32_e32 v36, 0, v36
	v_max_f32_e32 v37, 0, v37
	v_pk_mul_f32 v[40:41], v[32:33], v[32:33]
	v_max_f32_e32 v32, 0, v38
	v_max_f32_e32 v34, 0, v34
	v_max_f32_e32 v33, 0, v39
	v_max_f32_e32 v35, 0, v35
	v_pk_mul_f32 v[36:37], v[36:37], v[36:37]
	v_pk_mul_f32 v[38:39], v[32:33], v[32:33]
	v_pk_mul_f32 v[42:43], v[34:35], v[34:35]
	v_cvt_pk_bf16_f32 v32, v36, v37
	v_cvt_pk_bf16_f32 v33, v38, v39
	v_cvt_pk_bf16_f32 v34, v40, v41
;     __device__ __forceinline__ void operator()(const f32x4 (&acc)[2][2][4][2], const Unit& u, int wr, int wc, int fr, int fq) const {
;     ...
; #pragma unroll
;         for (int ai = 0; ai < 2; ++ai)
; #pragma unroll
;             for (int m = 0; m < 4; ++m) {
;                 const int r = u.pm * BM + ai * HALF + wr * 64 + m * 16 + fr;
;                 const float rs = rsqrtf(rsv[ai * 4 + m] * (1.0f / DM) + EPS);
; #pragma unroll
;                 for (int bj = 0; bj < 2; ++bj) {
;                     f32x4 a = acc[ai][bj][m][0] * rs, b = acc[ai][bj][m][1] * rs;
; #pragma unroll
;                     for (int t = 0; t < 4; ++t) { a[t] = fmaxf(a[t], 0.f); a[t] *= a[t]; b[t] = fmaxf(b[t], 0.f); b[t] *= b[t]; }
;                     st8bf(U + (size_t)r * FF + u.pn * BM + wc * 64 + bj * 32 + 8 * fq, a, b);
;                 }
	v_cvt_pk_bf16_f32 v35, v42, v43
	global_store_dwordx4 v[50:51], v[32:35], off offset:64
	s_nop 1
	v_mov_b32_e32 v34, v154
	v_mov_b32_e32 v35, v152
	v_mov_b32_e32 v152, v155
	v_pk_add_f32 v[34:35], v[34:35], v[152:153]
	v_lshlrev_b64 v[32:33], 13, v[146:147]
	v_pk_fma_f32 v[34:35], v[34:35], s[20:21], v[148:149] op_sel_hi:[1,0,0]
	v_lshl_add_u64 v[32:33], s[4:5], 0, v[32:33]
	v_mul_f32_e32 v36, 0x4b800000, v35
	v_cmp_gt_f32_e32 vcc, s56, v35
	v_lshl_add_u64 v[32:33], v[32:33], 0, s[34:35]
	v_lshl_add_u64 v[32:33], v[32:33], 0, s[12:13]
	v_cndmask_b32_e32 v35, v35, v36, vcc
	v_rsq_f32_e32 v35, v35
	v_lshl_add_u64 v[32:33], v[32:33], 0, v[136:137]
	v_mul_f32_e32 v36, 0x45800000, v35
	v_cndmask_b32_e32 v36, v35, v36, vcc
	v_pk_mul_f32 v[24:25], v[24:25], v[36:37] op_sel_hi:[1,0]
	v_pk_mul_f32 v[30:31], v[30:31], v[36:37] op_sel_hi:[1,0]
	v_pk_mul_f32 v[28:29], v[28:29], v[36:37] op_sel_hi:[1,0]
	v_pk_mul_f32 v[26:27], v[26:27], v[36:37] op_sel_hi:[1,0]
	v_max_f32_e32 v24, 0, v24
	v_max_f32_e32 v25, 0, v25
	v_max_f32_e32 v28, 0, v28
	v_max_f32_e32 v29, 0, v29
	v_pk_mul_f32 v[38:39], v[24:25], v[24:25]
	v_max_f32_e32 v24, 0, v30
	v_max_f32_e32 v26, 0, v26
	v_max_f32_e32 v25, 0, v31
	v_max_f32_e32 v27, 0, v27
	v_pk_mul_f32 v[28:29], v[28:29], v[28:29]
	v_pk_mul_f32 v[30:31], v[24:25], v[24:25]
	v_pk_mul_f32 v[40:41], v[26:27], v[26:27]
	v_pk_mul_f32 v[18:19], v[18:19], v[36:37] op_sel_hi:[1,0]
	v_cvt_pk_bf16_f32 v24, v28, v29
	v_cvt_pk_bf16_f32 v25, v30, v31
	v_cvt_pk_bf16_f32 v26, v38, v39
	v_cvt_pk_bf16_f32 v27, v40, v41
	v_pk_mul_f32 v[20:21], v[20:21], v[36:37] op_sel_hi:[1,0]
	v_pk_mul_f32 v[16:17], v[16:17], v[36:37] op_sel_hi:[1,0]
	v_max_f32_e32 v18, 0, v18
	v_max_f32_e32 v19, 0, v19
	global_store_dwordx4 v[32:33], v[24:27], off
	v_pk_mul_f32 v[22:23], v[22:23], v[36:37] op_sel_hi:[1,0]
	v_max_f32_e32 v20, 0, v20
	v_max_f32_e32 v16, 0, v16
	v_max_f32_e32 v21, 0, v21
	v_max_f32_e32 v17, 0, v17
	v_pk_mul_f32 v[26:27], v[18:19], v[18:19]
	v_mul_f32_e32 v18, 0x4b800000, v34
	v_cmp_gt_f32_e32 vcc, s56, v34
	v_pk_mul_f32 v[20:21], v[20:21], v[20:21]
	v_pk_mul_f32 v[24:25], v[16:17], v[16:17]
	v_max_f32_e32 v16, 0, v22
	v_max_f32_e32 v17, 0, v23
	v_cndmask_b32_e32 v18, v34, v18, vcc
	v_pk_mul_f32 v[22:23], v[16:17], v[16:17]
	v_cvt_pk_bf16_f32 v16, v20, v21
	v_rsq_f32_e32 v20, v18
	v_cvt_pk_bf16_f32 v17, v22, v23
	v_cvt_pk_bf16_f32 v18, v24, v25
	v_cvt_pk_bf16_f32 v19, v26, v27
	global_store_dwordx4 v[32:33], v[16:19], off offset:64
	s_nop 1
	v_mul_f32_e32 v16, 0x45800000, v20
	v_cndmask_b32_e32 v16, v20, v16, vcc
	v_pk_mul_f32 v[8:9], v[8:9], v[16:17] op_sel_hi:[1,0]
	v_pk_mul_f32 v[14:15], v[14:15], v[16:17] op_sel_hi:[1,0]
	v_max_f32_e32 v8, 0, v8
	v_max_f32_e32 v9, 0, v9
	v_lshlrev_b64 v[18:19], 13, v[144:145]
	v_pk_mul_f32 v[20:21], v[8:9], v[8:9]
	v_max_f32_e32 v8, 0, v14
	v_max_f32_e32 v9, 0, v15
	v_pk_mul_f32 v[12:13], v[12:13], v[16:17] op_sel_hi:[1,0]
	v_pk_mul_f32 v[10:11], v[10:11], v[16:17] op_sel_hi:[1,0]
	v_pk_mul_f32 v[14:15], v[8:9], v[8:9]
	v_lshl_add_u64 v[8:9], s[4:5], 0, v[18:19]
	v_max_f32_e32 v12, 0, v12
	v_max_f32_e32 v13, 0, v13
	v_max_f32_e32 v10, 0, v10
	v_max_f32_e32 v11, 0, v11
	v_lshl_add_u64 v[8:9], v[8:9], 0, s[34:35]
	v_pk_mul_f32 v[12:13], v[12:13], v[12:13]
	v_pk_mul_f32 v[22:23], v[10:11], v[10:11]
	v_lshl_add_u64 v[8:9], v[8:9], 0, s[12:13]
	v_pk_mul_f32 v[0:1], v[0:1], v[16:17] op_sel_hi:[1,0]
	v_lshl_add_u64 v[18:19], v[8:9], 0, v[136:137]
	v_cvt_pk_bf16_f32 v8, v12, v13
	v_cvt_pk_bf16_f32 v9, v14, v15
	v_cvt_pk_bf16_f32 v10, v20, v21
	v_cvt_pk_bf16_f32 v11, v22, v23
	v_pk_mul_f32 v[6:7], v[6:7], v[16:17] op_sel_hi:[1,0]
	v_pk_mul_f32 v[4:5], v[4:5], v[16:17] op_sel_hi:[1,0]
	v_pk_mul_f32 v[2:3], v[2:3], v[16:17] op_sel_hi:[1,0]
	v_max_f32_e32 v0, 0, v0
	v_max_f32_e32 v1, 0, v1
	global_store_dwordx4 v[18:19], v[8:11], off
	v_max_f32_e32 v4, 0, v4
	v_max_f32_e32 v5, 0, v5
	v_pk_mul_f32 v[8:9], v[0:1], v[0:1]
	v_max_f32_e32 v0, 0, v6
	v_max_f32_e32 v2, 0, v2
	v_max_f32_e32 v1, 0, v7
	v_max_f32_e32 v3, 0, v3
	v_pk_mul_f32 v[4:5], v[4:5], v[4:5]
	v_pk_mul_f32 v[6:7], v[0:1], v[0:1]
	v_pk_mul_f32 v[10:11], v[2:3], v[2:3]
	v_cvt_pk_bf16_f32 v0, v4, v5
	v_cvt_pk_bf16_f32 v1, v6, v7
	v_cvt_pk_bf16_f32 v2, v8, v9
	v_cvt_pk_bf16_f32 v3, v10, v11
	s_andn2_b64 vcc, exec, s[0:1]
	s_mov_b64 s[0:1], -1
	global_store_dwordx4 v[18:19], v[0:3], off offset:64
	s_cbranch_vccnz .LBB0_973
	s_andn2_b64 vcc, exec, s[14:15]
	s_cbranch_vccnz .LBB0_972
	s_barrier
	s_branch .LBB0_972
